# og phase: 3-round ds_bpermute head reductions replaced by DPP quad_perm / row_half_mirror adds
# baseline (speedup 1.0000x reference)
.LBB0_694:
	s_ashr_i32 s1, s0, 31
	s_lshl_b64 s[28:29], s[0:1], 11
	v_lshl_add_u64 v[0:1], v[56:57], 0, s[28:29]
	global_load_dwordx4 v[82:85], v[0:1], off offset:16
	v_lshl_add_u64 v[2:3], v[58:59], 0, s[28:29]
	global_load_dwordx4 v[86:89], v[2:3], off offset:16
	global_load_dwordx4 v[90:93], v[0:1], off
	global_load_dwordx4 v[94:97], v[2:3], off
	s_add_i32 s2, s0, 1
	s_ashr_i32 s3, s2, 31
	s_lshl_b64 s[24:25], s[2:3], 11
	v_lshl_add_u64 v[8:9], v[56:57], 0, s[24:25]
	global_load_dwordx4 v[0:3], v[60:61], off offset:48
	global_load_dwordx4 v[4:7], v[60:61], off offset:32
	global_load_dwordx4 v[98:101], v[8:9], off
	global_load_dwordx4 v[102:105], v[8:9], off offset:16
	s_nop 0
	global_load_dwordx4 v[8:11], v[60:61], off offset:16
	global_load_dwordx4 v[16:19], v[60:61], off
	s_add_i32 s8, s0, 2
	s_add_i32 s34, s0, 3
	s_ashr_i32 s9, s8, 31
	s_ashr_i32 s35, s34, 31
	s_lshl_b64 s[8:9], s[8:9], 11
	s_lshl_b64 s[2:3], s[34:35], 11
	v_lshl_add_u64 v[12:13], v[58:59], 0, s[24:25]
	v_lshl_add_u64 v[14:15], v[56:57], 0, s[8:9]
	v_lshl_add_u64 v[20:21], v[58:59], 0, s[8:9]
	v_lshl_add_u64 v[22:23], v[56:57], 0, s[2:3]
	v_lshl_add_u64 v[64:65], v[58:59], 0, s[2:3]
	global_load_dwordx4 v[52:55], v[12:13], off
	global_load_dwordx4 v[48:51], v[12:13], off offset:16
	global_load_dwordx4 v[40:43], v[14:15], off
	global_load_dwordx4 v[44:47], v[14:15], off offset:16
	global_load_dwordx4 v[36:39], v[20:21], off
	global_load_dwordx4 v[32:35], v[20:21], off offset:16
	global_load_dwordx4 v[24:27], v[22:23], off
	global_load_dwordx4 v[28:31], v[22:23], off offset:16
	s_nop 0
	global_load_dwordx4 v[20:23], v[64:65], off
	global_load_dwordx4 v[12:15], v[64:65], off offset:16
	s_add_i32 s18, s18, s19
	s_add_i32 s0, s0, s30
	s_cmpk_lt_i32 s18, 0x2000
	s_waitcnt vmcnt(18)
	v_lshlrev_b32_e32 v68, 16, v88
	v_lshlrev_b32_e32 v70, 16, v83
	v_lshlrev_b32_e32 v74, 16, v82
	v_lshlrev_b32_e32 v64, 16, v85
	v_and_b32_e32 v65, 0xffff0000, v85
	v_and_b32_e32 v69, 0xffff0000, v88
	v_and_b32_e32 v71, 0xffff0000, v83
	v_and_b32_e32 v75, 0xffff0000, v82
	v_mul_f32_e32 v88, v70, v70
	v_mul_f32_e32 v112, v74, v74
	v_lshlrev_b32_e32 v66, 16, v84
	v_and_b32_e32 v67, 0xffff0000, v84
	v_lshlrev_b32_e32 v72, 16, v87
	v_and_b32_e32 v73, 0xffff0000, v87
	v_lshlrev_b32_e32 v76, 16, v86
	v_and_b32_e32 v77, 0xffff0000, v86
	s_waitcnt vmcnt(17)
	v_lshlrev_b32_e32 v82, 16, v93
	v_and_b32_e32 v83, 0xffff0000, v93
	s_waitcnt vmcnt(16)
	v_lshlrev_b32_e32 v84, 16, v97
	v_and_b32_e32 v85, 0xffff0000, v97
	v_lshlrev_b32_e32 v86, 16, v92
	v_and_b32_e32 v87, 0xffff0000, v92
	v_lshlrev_b32_e32 v92, 16, v96
	v_and_b32_e32 v93, 0xffff0000, v96
	v_lshlrev_b32_e32 v96, 16, v91
	v_and_b32_e32 v97, 0xffff0000, v91
	v_lshlrev_b32_e32 v106, 16, v95
	v_and_b32_e32 v107, 0xffff0000, v95
	v_lshlrev_b32_e32 v108, 16, v90
	v_and_b32_e32 v109, 0xffff0000, v90
	v_lshlrev_b32_e32 v90, 16, v94
	v_and_b32_e32 v91, 0xffff0000, v94
	v_pk_mul_f32 v[94:95], v[64:65], v[64:65]
	v_pk_fma_f32 v[122:123], v[70:71], v[70:71], v[88:89] op_sel_hi:[1,1,0]
	v_pk_fma_f32 v[112:113], v[74:75], v[74:75], v[112:113] op_sel_hi:[1,1,0]
	v_mov_b32_e32 v122, v95
	v_mov_b32_e32 v112, v94
	v_mov_b32_e32 v116, v87
	v_mov_b32_e32 v117, v83
	v_mov_b32_e32 v120, v109
	v_mov_b32_e32 v121, v97
	v_pk_add_f32 v[94:95], v[112:113], v[122:123]
	s_waitcnt vmcnt(13)
	v_and_b32_e32 v123, 0xffff0000, v101
	v_and_b32_e32 v125, 0xffff0000, v100
	v_mov_b32_e32 v114, v86
	v_mov_b32_e32 v115, v82
	v_mov_b32_e32 v118, v108
	v_mov_b32_e32 v119, v96
	v_pk_mul_f32 v[116:117], v[116:117], v[116:117]
	v_pk_mul_f32 v[120:121], v[120:121], v[120:121]
	v_lshlrev_b32_e32 v122, 16, v101
	v_lshlrev_b32_e32 v124, 16, v100
	v_mov_b32_e32 v126, v125
	v_mov_b32_e32 v127, v123
	v_pk_fma_f32 v[114:115], v[114:115], v[114:115], v[116:117]
	v_pk_fma_f32 v[116:117], v[118:119], v[118:119], v[120:121]
	v_mov_b32_e32 v100, v124
	v_mov_b32_e32 v101, v122
	v_pk_mul_f32 v[126:127], v[126:127], v[126:127]
	v_pk_mul_f32 v[110:111], v[66:67], v[66:67]
	v_pk_add_f32 v[114:115], v[114:115], v[114:115] op_sel_hi:[0,1]
	v_pk_add_f32 v[116:117], v[116:117], v[116:117] op_sel_hi:[0,1]
	v_pk_fma_f32 v[100:101], v[100:101], v[100:101], v[126:127]
	v_and_b32_e32 v127, 0xffff0000, v99
	v_and_b32_e32 v129, 0xffff0000, v98
	v_mov_b32_e32 v116, v110
	v_mov_b32_e32 v114, v111
	v_lshlrev_b32_e32 v126, 16, v99
	v_lshlrev_b32_e32 v128, 16, v98
	v_mov_b32_e32 v130, v129
	v_mov_b32_e32 v131, v127
	v_pk_add_f32 v[110:111], v[116:117], v[114:115]
	s_waitcnt vmcnt(12)
	v_lshlrev_b32_e32 v116, 16, v103
	v_lshlrev_b32_e32 v120, 16, v102
	v_mov_b32_e32 v98, v128
	v_mov_b32_e32 v99, v126
	v_pk_mul_f32 v[130:131], v[130:131], v[130:131]
	v_pk_add_f32 v[94:95], v[110:111], v[94:95]
	v_lshlrev_b32_e32 v110, 16, v105
	v_and_b32_e32 v111, 0xffff0000, v105
	v_lshlrev_b32_e32 v114, 16, v104
	v_and_b32_e32 v115, 0xffff0000, v104
	v_and_b32_e32 v117, 0xffff0000, v103
	v_mul_f32_e32 v118, v116, v116
	v_and_b32_e32 v121, 0xffff0000, v102
	v_mul_f32_e32 v102, v120, v120
	v_pk_fma_f32 v[98:99], v[98:99], v[98:99], v[130:131]
	v_pk_mul_f32 v[112:113], v[110:111], v[110:111]
	v_pk_mul_f32 v[104:105], v[114:115], v[114:115]
	v_pk_fma_f32 v[118:119], v[116:117], v[116:117], v[118:119] op_sel_hi:[1,1,0]
	v_pk_fma_f32 v[102:103], v[120:121], v[120:121], v[102:103] op_sel_hi:[1,1,0]
	v_pk_add_f32 v[100:101], v[100:101], v[100:101] op_sel_hi:[0,1]
	v_pk_add_f32 v[98:99], v[98:99], v[98:99] op_sel_hi:[0,1]
	v_mov_b32_e32 v102, v112
	v_mov_b32_e32 v118, v113
	v_mov_b32_e32 v98, v104
	v_mov_b32_e32 v100, v105
	v_pk_add_f32 v[102:103], v[102:103], v[118:119]
	v_pk_add_f32 v[98:99], v[98:99], v[100:101]
	v_mov_b32_e32 v101, v94
	v_pk_add_f32 v[98:99], v[98:99], v[102:103]
	s_waitcnt vmcnt(8)
	v_lshlrev_b32_e32 v104, 16, v49
	v_mov_b32_e32 v100, v98
	v_mov_b32_e32 v94, v99
	v_pk_add_f32 v[94:95], v[100:101], v[94:95]
	v_and_b32_e32 v105, 0xffff0000, v49
	v_lshlrev_b32_e32 v112, 16, v48
	v_and_b32_e32 v113, 0xffff0000, v48
	v_lshl_add_u64 v[100:101], v[62:63], 0, s[28:29]
	s_waitcnt lgkmcnt(0)
	s_nop 1
	v_add_f32_dpp v94, v94, v94 quad_perm:[1,0,3,2] row_mask:0xf bank_mask:0xf
	v_add_f32_dpp v95, v95, v95 quad_perm:[1,0,3,2] row_mask:0xf bank_mask:0xf
	s_mov_b32 s28, 0x358637bd
	v_lshlrev_b32_e32 v118, 16, v55
	v_and_b32_e32 v119, 0xffff0000, v55
	v_lshlrev_b32_e32 v102, 16, v50
	s_waitcnt lgkmcnt(0)
	s_nop 1
	v_add_f32_dpp v48, v94, v94 quad_perm:[2,3,0,1] row_mask:0xf bank_mask:0xf
	v_add_f32_dpp v49, v95, v95 quad_perm:[2,3,0,1] row_mask:0xf bank_mask:0xf
	v_lshlrev_b32_e32 v98, 16, v54
	v_and_b32_e32 v99, 0xffff0000, v54
	v_and_b32_e32 v103, 0xffff0000, v50
	v_lshlrev_b32_e32 v132, 16, v52
	s_waitcnt lgkmcnt(0)
	s_nop 1
	v_add_f32_dpp v54, v48, v48 row_half_mirror row_mask:0xf bank_mask:0xf
	v_add_f32_dpp v55, v49, v49 row_half_mirror row_mask:0xf bank_mask:0xf
	v_mov_b64_e32 v[48:49], s[28:29]
	v_pk_fma_f32 v[94:95], v[54:55], s[36:37], v[48:49] op_sel_hi:[1,0,0]
	v_and_b32_e32 v133, 0xffff0000, v52
	v_mul_f32_e32 v50, 0x4b800000, v95
	v_cmp_gt_f32_e32 vcc, s33, v95
	v_lshlrev_b32_e32 v130, 16, v53
	v_and_b32_e32 v131, 0xffff0000, v53
	v_cndmask_b32_e32 v50, v95, v50, vcc
	v_rsq_f32_e32 v50, v50
	v_lshlrev_b32_e32 v88, 16, v89
	v_and_b32_e32 v89, 0xffff0000, v89
	s_waitcnt vmcnt(3)
	v_and_b32_e32 v95, 0xffff0000, v26
	v_mul_f32_e32 v52, 0x45800000, v50
	v_cndmask_b32_e32 v50, v50, v52, vcc
	v_pk_mul_f32 v[52:53], v[50:51], v[108:109] op_sel_hi:[0,1]
	v_pk_mul_f32 v[54:55], v[50:51], v[96:97] op_sel_hi:[0,1]
	v_pk_mul_f32 v[52:53], v[16:17], v[52:53]
	v_pk_mul_f32 v[54:55], v[18:19], v[54:55]
	v_pk_mul_f32 v[52:53], v[52:53], v[90:91]
	v_pk_mul_f32 v[54:55], v[54:55], v[106:107]
	v_cvt_pk_bf16_f32 v52, v52, v53
	v_cvt_pk_bf16_f32 v53, v54, v55
	v_pk_mul_f32 v[54:55], v[50:51], v[86:87] op_sel_hi:[0,1]
	v_pk_mul_f32 v[82:83], v[50:51], v[82:83] op_sel_hi:[0,1]
	v_pk_mul_f32 v[74:75], v[50:51], v[74:75] op_sel_hi:[0,1]
	v_pk_mul_f32 v[70:71], v[50:51], v[70:71] op_sel_hi:[0,1]
	v_pk_mul_f32 v[66:67], v[50:51], v[66:67] op_sel_hi:[0,1]
	v_pk_mul_f32 v[64:65], v[50:51], v[64:65] op_sel_hi:[0,1]
	v_mul_f32_e32 v50, 0x4b800000, v94
	v_cmp_gt_f32_e32 vcc, s33, v94
	v_pk_mul_f32 v[54:55], v[8:9], v[54:55]
	v_pk_mul_f32 v[82:83], v[10:11], v[82:83]
	v_cndmask_b32_e32 v50, v94, v50, vcc
	v_rsq_f32_e32 v50, v50
	v_pk_mul_f32 v[54:55], v[54:55], v[92:93]
	v_pk_mul_f32 v[82:83], v[82:83], v[84:85]
	v_pk_mul_f32 v[74:75], v[4:5], v[74:75]
	v_pk_mul_f32 v[70:71], v[6:7], v[70:71]
	v_pk_mul_f32 v[66:67], v[0:1], v[66:67]
	v_pk_mul_f32 v[64:65], v[2:3], v[64:65]
	v_cvt_pk_bf16_f32 v54, v54, v55
	v_cvt_pk_bf16_f32 v55, v82, v83
	v_pk_mul_f32 v[74:75], v[74:75], v[76:77]
	v_pk_mul_f32 v[72:73], v[70:71], v[72:73]
	v_pk_mul_f32 v[66:67], v[66:67], v[68:69]
	v_pk_mul_f32 v[64:65], v[64:65], v[88:89]
	v_cvt_pk_bf16_f32 v70, v74, v75
	v_cvt_pk_bf16_f32 v71, v72, v73
	v_cvt_pk_bf16_f32 v72, v66, v67
	v_cvt_pk_bf16_f32 v73, v64, v65
	global_store_dwordx4 v[100:101], v[52:55], off
	global_store_dwordx4 v[100:101], v[70:73], off offset:16
	v_and_b32_e32 v83, 0xffff0000, v42
	v_mul_f32_e32 v52, 0x45800000, v50
	v_cndmask_b32_e32 v50, v50, v52, vcc
	v_pk_mul_f32 v[52:53], v[50:51], v[128:129] op_sel_hi:[0,1]
	v_pk_mul_f32 v[54:55], v[50:51], v[126:127] op_sel_hi:[0,1]
	v_pk_mul_f32 v[52:53], v[16:17], v[52:53]
	v_pk_mul_f32 v[54:55], v[18:19], v[54:55]
	v_pk_mul_f32 v[52:53], v[52:53], v[132:133]
	v_pk_mul_f32 v[54:55], v[54:55], v[130:131]
	v_cvt_pk_bf16_f32 v52, v52, v53
	v_cvt_pk_bf16_f32 v53, v54, v55
	v_pk_mul_f32 v[54:55], v[50:51], v[124:125] op_sel_hi:[0,1]
	v_pk_mul_f32 v[64:65], v[50:51], v[122:123] op_sel_hi:[0,1]
	v_pk_mul_f32 v[54:55], v[8:9], v[54:55]
	v_pk_mul_f32 v[64:65], v[10:11], v[64:65]
	v_pk_mul_f32 v[54:55], v[54:55], v[98:99]
	v_pk_mul_f32 v[64:65], v[64:65], v[118:119]
	v_cvt_pk_bf16_f32 v54, v54, v55
	v_cvt_pk_bf16_f32 v55, v64, v65
	v_pk_mul_f32 v[64:65], v[50:51], v[120:121] op_sel_hi:[0,1]
	v_pk_mul_f32 v[66:67], v[50:51], v[116:117] op_sel_hi:[0,1]
	v_pk_mul_f32 v[64:65], v[4:5], v[64:65]
	v_pk_mul_f32 v[66:67], v[6:7], v[66:67]
	v_pk_mul_f32 v[64:65], v[64:65], v[112:113]
	v_pk_mul_f32 v[66:67], v[66:67], v[104:105]
	v_cvt_pk_bf16_f32 v64, v64, v65
	v_cvt_pk_bf16_f32 v65, v66, v67
	v_pk_mul_f32 v[66:67], v[50:51], v[114:115] op_sel_hi:[0,1]
	v_pk_mul_f32 v[68:69], v[50:51], v[110:111] op_sel_hi:[0,1]
	v_lshlrev_b32_e32 v70, 16, v33
	v_and_b32_e32 v71, 0xffff0000, v33
	v_and_b32_e32 v33, 0xffff0000, v43
	v_pk_mul_f32 v[66:67], v[0:1], v[66:67]
	v_pk_mul_f32 v[68:69], v[2:3], v[68:69]
	v_lshlrev_b32_e32 v50, 16, v51
	v_and_b32_e32 v51, 0xffff0000, v51
	v_lshlrev_b32_e32 v74, 16, v32
	v_and_b32_e32 v75, 0xffff0000, v32
	v_lshlrev_b32_e32 v32, 16, v43
	v_lshlrev_b32_e32 v82, 16, v42
	v_mov_b32_e32 v84, v83
	v_mov_b32_e32 v85, v33
	v_pk_mul_f32 v[66:67], v[66:67], v[102:103]
	v_pk_mul_f32 v[50:51], v[68:69], v[50:51]
	v_mov_b32_e32 v42, v82
	v_mov_b32_e32 v43, v32
	v_pk_mul_f32 v[84:85], v[84:85], v[84:85]
	v_cvt_pk_bf16_f32 v66, v66, v67
	v_cvt_pk_bf16_f32 v67, v50, v51
	v_lshl_add_u64 v[50:51], v[62:63], 0, s[24:25]
	v_pk_fma_f32 v[42:43], v[42:43], v[42:43], v[84:85]
	global_store_dwordx4 v[50:51], v[52:55], off
	global_store_dwordx4 v[50:51], v[64:67], off offset:16
	v_lshlrev_b32_e32 v76, 16, v39
	v_and_b32_e32 v77, 0xffff0000, v39
	v_lshlrev_b32_e32 v66, 16, v45
	v_lshlrev_b32_e32 v84, 16, v38
	v_and_b32_e32 v85, 0xffff0000, v38
	v_pk_add_f32 v[38:39], v[42:43], v[42:43] op_sel_hi:[0,1]
	v_and_b32_e32 v43, 0xffff0000, v41
	v_and_b32_e32 v89, 0xffff0000, v40
	v_and_b32_e32 v93, 0xffff0000, v27
	v_lshlrev_b32_e32 v50, 16, v47
	v_and_b32_e32 v51, 0xffff0000, v47
	v_lshlrev_b32_e32 v52, 16, v46
	v_and_b32_e32 v53, 0xffff0000, v46
	v_lshlrev_b32_e32 v46, 16, v34
	v_and_b32_e32 v47, 0xffff0000, v34
	v_and_b32_e32 v67, 0xffff0000, v45
	v_mul_f32_e32 v34, v66, v66
	v_lshlrev_b32_e32 v72, 16, v44
	v_lshlrev_b32_e32 v42, 16, v41
	v_lshlrev_b32_e32 v88, 16, v40
	v_mov_b32_e32 v90, v89
	v_mov_b32_e32 v91, v43
	v_lshlrev_b32_e32 v92, 16, v27
	v_lshlrev_b32_e32 v94, 16, v26
	v_mov_b32_e32 v96, v95
	v_mov_b32_e32 v97, v93
	v_pk_fma_f32 v[68:69], v[66:67], v[66:67], v[34:35] op_sel_hi:[1,1,0]
	v_and_b32_e32 v73, 0xffff0000, v44
	v_mul_f32_e32 v34, v72, v72
	v_mov_b32_e32 v40, v88
	v_mov_b32_e32 v41, v42
	v_pk_mul_f32 v[90:91], v[90:91], v[90:91]
	v_mov_b32_e32 v26, v94
	v_mov_b32_e32 v27, v92
	v_pk_mul_f32 v[96:97], v[96:97], v[96:97]
	v_pk_mul_f32 v[54:55], v[50:51], v[50:51]
	v_pk_fma_f32 v[44:45], v[72:73], v[72:73], v[34:35] op_sel_hi:[1,1,0]
	v_pk_fma_f32 v[40:41], v[40:41], v[40:41], v[90:91]
	v_pk_fma_f32 v[26:27], v[26:27], v[26:27], v[96:97]
	v_and_b32_e32 v97, 0xffff0000, v25
	v_and_b32_e32 v99, 0xffff0000, v24
	v_pk_mul_f32 v[64:65], v[52:53], v[52:53]
	v_lshlrev_b32_e32 v86, 16, v37
	v_and_b32_e32 v87, 0xffff0000, v37
	v_lshlrev_b32_e32 v90, 16, v36
	v_and_b32_e32 v91, 0xffff0000, v36
	v_pk_add_f32 v[36:37], v[40:41], v[40:41] op_sel_hi:[0,1]
	v_mov_b32_e32 v44, v54
	v_mov_b32_e32 v68, v55
	v_lshlrev_b32_e32 v96, 16, v25
	v_lshlrev_b32_e32 v98, 16, v24
	v_mov_b32_e32 v100, v99
	v_mov_b32_e32 v101, v97
	v_pk_add_f32 v[40:41], v[44:45], v[68:69]
	v_mov_b32_e32 v36, v64
	v_mov_b32_e32 v38, v65
	s_waitcnt vmcnt(6)
	v_lshlrev_b32_e32 v54, 16, v29
	v_lshlrev_b32_e32 v68, 16, v28
	v_mov_b32_e32 v24, v98
	v_mov_b32_e32 v25, v96
	v_pk_mul_f32 v[100:101], v[100:101], v[100:101]
	v_pk_add_f32 v[36:37], v[36:37], v[38:39]
	v_lshlrev_b32_e32 v38, 16, v31
	v_and_b32_e32 v39, 0xffff0000, v31
	v_lshlrev_b32_e32 v44, 16, v30
	v_and_b32_e32 v45, 0xffff0000, v30
	v_and_b32_e32 v55, 0xffff0000, v29
	v_mul_f32_e32 v64, v54, v54
	v_and_b32_e32 v69, 0xffff0000, v28
	v_mul_f32_e32 v28, v68, v68
	v_pk_fma_f32 v[24:25], v[24:25], v[24:25], v[100:101]
	v_pk_add_f32 v[36:37], v[36:37], v[40:41]
	v_pk_mul_f32 v[40:41], v[38:39], v[38:39]
	v_pk_mul_f32 v[30:31], v[44:45], v[44:45]
	v_pk_fma_f32 v[64:65], v[54:55], v[54:55], v[64:65] op_sel_hi:[1,1,0]
	v_pk_fma_f32 v[28:29], v[68:69], v[68:69], v[28:29] op_sel_hi:[1,1,0]
	v_pk_add_f32 v[26:27], v[26:27], v[26:27] op_sel_hi:[0,1]
	v_pk_add_f32 v[24:25], v[24:25], v[24:25] op_sel_hi:[0,1]
	v_mov_b32_e32 v28, v40
	v_mov_b32_e32 v64, v41
	v_mov_b32_e32 v24, v30
	v_mov_b32_e32 v26, v31
	v_pk_add_f32 v[28:29], v[28:29], v[64:65]
	v_pk_add_f32 v[24:25], v[24:25], v[26:27]
	v_mov_b32_e32 v27, v36
	v_pk_add_f32 v[24:25], v[24:25], v[28:29]
	s_waitcnt vmcnt(4)
	v_lshlrev_b32_e32 v40, 16, v12
	v_mov_b32_e32 v26, v24
	v_mov_b32_e32 v36, v25
	v_pk_add_f32 v[24:25], v[26:27], v[36:37]
	v_lshlrev_b32_e32 v36, 16, v13
	v_and_b32_e32 v37, 0xffff0000, v13
	v_and_b32_e32 v41, 0xffff0000, v12
	v_lshlrev_b32_e32 v12, 16, v23
	s_waitcnt lgkmcnt(0)
	s_nop 1
	v_add_f32_dpp v24, v24, v24 quad_perm:[1,0,3,2] row_mask:0xf bank_mask:0xf
	v_add_f32_dpp v25, v25, v25 quad_perm:[1,0,3,2] row_mask:0xf bank_mask:0xf
	v_and_b32_e32 v13, 0xffff0000, v23
	v_lshlrev_b32_e32 v64, 16, v22
	v_and_b32_e32 v65, 0xffff0000, v22
	v_lshlrev_b32_e32 v30, 16, v14
	s_waitcnt lgkmcnt(0)
	s_nop 1
	v_add_f32_dpp v24, v24, v24 quad_perm:[2,3,0,1] row_mask:0xf bank_mask:0xf
	v_add_f32_dpp v25, v25, v25 quad_perm:[2,3,0,1] row_mask:0xf bank_mask:0xf
	v_and_b32_e32 v31, 0xffff0000, v14
	v_lshlrev_b32_e32 v102, 16, v20
	v_and_b32_e32 v103, 0xffff0000, v20
	v_lshlrev_b32_e32 v100, 16, v21
	s_waitcnt lgkmcnt(0)
	s_nop 1
	v_add_f32_dpp v22, v24, v24 row_half_mirror row_mask:0xf bank_mask:0xf
	v_add_f32_dpp v23, v25, v25 row_half_mirror row_mask:0xf bank_mask:0xf
	v_and_b32_e32 v101, 0xffff0000, v21
	v_pk_fma_f32 v[48:49], v[22:23], s[36:37], v[48:49] op_sel_hi:[1,0,0]
	v_lshlrev_b32_e32 v34, 16, v35
	v_mul_f32_e32 v14, 0x4b800000, v49
	v_cmp_gt_f32_e32 vcc, s33, v49
	v_and_b32_e32 v35, 0xffff0000, v35
	v_lshl_add_u64 v[28:29], v[62:63], 0, s[8:9]
	v_cndmask_b32_e32 v14, v49, v14, vcc
	v_rsq_f32_e32 v14, v14
	s_nop 0
	v_mul_f32_e32 v20, 0x45800000, v14
	v_cndmask_b32_e32 v14, v14, v20, vcc
	v_pk_mul_f32 v[20:21], v[14:15], v[88:89] op_sel_hi:[0,1]
	v_pk_mul_f32 v[22:23], v[14:15], v[42:43] op_sel_hi:[0,1]
	v_pk_mul_f32 v[20:21], v[16:17], v[20:21]
	v_pk_mul_f32 v[22:23], v[18:19], v[22:23]
	v_pk_mul_f32 v[20:21], v[20:21], v[90:91]
	v_pk_mul_f32 v[22:23], v[22:23], v[86:87]
	v_cvt_pk_bf16_f32 v20, v20, v21
	v_cvt_pk_bf16_f32 v21, v22, v23
	v_pk_mul_f32 v[22:23], v[14:15], v[82:83] op_sel_hi:[0,1]
	v_pk_mul_f32 v[24:25], v[14:15], v[32:33] op_sel_hi:[0,1]
	v_pk_mul_f32 v[22:23], v[8:9], v[22:23]
	v_pk_mul_f32 v[24:25], v[10:11], v[24:25]
	v_pk_mul_f32 v[22:23], v[22:23], v[84:85]
	v_pk_mul_f32 v[24:25], v[24:25], v[76:77]
	v_cvt_pk_bf16_f32 v22, v22, v23
	v_cvt_pk_bf16_f32 v23, v24, v25
	v_pk_mul_f32 v[24:25], v[14:15], v[72:73] op_sel_hi:[0,1]
	v_pk_mul_f32 v[26:27], v[14:15], v[66:67] op_sel_hi:[0,1]
	v_pk_mul_f32 v[24:25], v[4:5], v[24:25]
	v_pk_mul_f32 v[26:27], v[6:7], v[26:27]
	v_pk_mul_f32 v[24:25], v[24:25], v[74:75]
	v_pk_mul_f32 v[26:27], v[26:27], v[70:71]
	v_cvt_pk_bf16_f32 v24, v24, v25
	v_cvt_pk_bf16_f32 v25, v26, v27
	v_pk_mul_f32 v[26:27], v[14:15], v[52:53] op_sel_hi:[0,1]
	v_pk_mul_f32 v[32:33], v[14:15], v[50:51] op_sel_hi:[0,1]
	v_mul_f32_e32 v14, 0x4b800000, v48
	v_cmp_gt_f32_e32 vcc, s33, v48
	v_pk_mul_f32 v[26:27], v[0:1], v[26:27]
	v_pk_mul_f32 v[32:33], v[2:3], v[32:33]
	v_cndmask_b32_e32 v14, v48, v14, vcc
	v_rsq_f32_e32 v14, v14
	v_pk_mul_f32 v[26:27], v[26:27], v[46:47]
	v_pk_mul_f32 v[32:33], v[32:33], v[34:35]
	v_cvt_pk_bf16_f32 v26, v26, v27
	v_cvt_pk_bf16_f32 v27, v32, v33
	global_store_dwordx4 v[28:29], v[20:23], off
	global_store_dwordx4 v[28:29], v[24:27], off offset:16
	s_nop 0
	v_mul_f32_e32 v20, 0x45800000, v14
	v_cndmask_b32_e32 v14, v14, v20, vcc
	v_pk_mul_f32 v[20:21], v[14:15], v[98:99] op_sel_hi:[0,1]
	v_pk_mul_f32 v[16:17], v[16:17], v[20:21]
	v_pk_mul_f32 v[20:21], v[14:15], v[96:97] op_sel_hi:[0,1]
	v_pk_mul_f32 v[18:19], v[18:19], v[20:21]
	v_pk_mul_f32 v[16:17], v[16:17], v[102:103]
	v_pk_mul_f32 v[18:19], v[18:19], v[100:101]
	v_cvt_pk_bf16_f32 v16, v16, v17
	v_cvt_pk_bf16_f32 v17, v18, v19
	v_pk_mul_f32 v[18:19], v[14:15], v[94:95] op_sel_hi:[0,1]
	v_pk_mul_f32 v[8:9], v[8:9], v[18:19]
	v_pk_mul_f32 v[18:19], v[14:15], v[92:93] op_sel_hi:[0,1]
	v_pk_mul_f32 v[8:9], v[8:9], v[64:65]
	v_pk_mul_f32 v[10:11], v[10:11], v[18:19]
	v_cvt_pk_bf16_f32 v18, v8, v9
	v_pk_mul_f32 v[8:9], v[14:15], v[68:69] op_sel_hi:[0,1]
	v_pk_mul_f32 v[4:5], v[4:5], v[8:9]
	v_pk_mul_f32 v[8:9], v[14:15], v[54:55] op_sel_hi:[0,1]
	v_pk_mul_f32 v[6:7], v[6:7], v[8:9]
	v_pk_mul_f32 v[4:5], v[4:5], v[40:41]
	v_pk_mul_f32 v[6:7], v[6:7], v[36:37]
	v_cvt_pk_bf16_f32 v4, v4, v5
	v_cvt_pk_bf16_f32 v5, v6, v7
	v_pk_mul_f32 v[6:7], v[14:15], v[44:45] op_sel_hi:[0,1]
	v_pk_mul_f32 v[0:1], v[0:1], v[6:7]
	v_pk_mul_f32 v[6:7], v[14:15], v[38:39] op_sel_hi:[0,1]
	v_pk_mul_f32 v[2:3], v[2:3], v[6:7]
	v_lshlrev_b32_e32 v6, 16, v15
	v_and_b32_e32 v7, 0xffff0000, v15
	v_pk_mul_f32 v[10:11], v[10:11], v[12:13]
	v_pk_mul_f32 v[0:1], v[0:1], v[30:31]
	v_pk_mul_f32 v[2:3], v[2:3], v[6:7]
	v_cvt_pk_bf16_f32 v19, v10, v11
	v_cvt_pk_bf16_f32 v6, v0, v1
	v_cvt_pk_bf16_f32 v7, v2, v3
	v_lshl_add_u64 v[0:1], v[62:63], 0, s[2:3]
	global_store_dwordx4 v[0:1], v[16:19], off
	global_store_dwordx4 v[0:1], v[4:7], off offset:16
	s_cbranch_scc1 .LBB0_694
